# pipelined attention v3: persistent -m accumulator-init block in v240-255 (alloc 256), stale MFMA-distance nops dropped from softmax block
# speedup vs baseline: 1.0019x; 1.0019x over previous
; DI int opaque_tid() { int t = threadIdx.x; asm volatile("" : "+v"(t)); return t; }
; DI void attn_item(const Params& p, unsigned char* lds, int b, int hd, int qb, float lam) {
;     const int tid = opaque_tid(), lane = tid & 63, wave = tid >> 6, l31 = lane & 31, h = lane >> 5;
;     const int sub = wave >> 2, rt = wave & 3;
;     const bf16_t* aq = (const bf16_t*)((unsigned char*)p.out + DO_AQ);
;     const bf16_t* ak = (const bf16_t*)(p.ws + OFF_AK);
;     const bf16_t* avT = (const bf16_t*)(p.ws + OFF_AVT);
;     const bf16_t* akm = (const bf16_t*)(p.ws + OFF_AKM);
;     const bf16_t* avTm = (const bf16_t*)(p.ws + OFF_AVTM);
;     bf16_t* az = (bf16_t*)(p.ws + OFF_AZ);
;     const int qs = qb * 128 + rt * 32 + l31;
;     const size_t grow = (size_t)b * 4096 + qs;
;     bf16x8 qf[4];
; #pragma unroll
;     for (int ks = 0; ks < 4; ++ks) qf[ks] = *(const bf16x8*)(aq + grow * 1024 + hd * 128 + sub * 64 + ks * 16 + 8 * h);
;     f32x16 O[4];
; #pragma unroll
;     for (int d = 0; d < 4; ++d)
; #pragma unroll
;         for (int i = 0; i < 16; ++i) O[d][i] = 0.f;
;     float m = 0.f, l = 0.f;
;     const int T = 2 * qb + 3;
;     u32x4 k0r[2], v0r[2];
;     const int krow_ = tid >> 4, kc_ = tid & 15, vdv_ = tid >> 3, vc_ = tid & 7;
;     const bf16_t* kp = ak + ((size_t)b * 4096 + krow_) * 1024 + hd * 128 + kc_ * 8;
;     const bf16_t* vp_ = avT + ((size_t)(b * 8 + hd) * 128 + vdv_) * 4096 + vc_ * 8;
;     ...
;     {
;         const bf16_t* km_ = akm + (size_t)krow_ * 1024 + hd * 128 + kc_ * 8;
;         k0r[0] = *(const u32x4*)km_; k0r[1] = *(const u32x4*)(km_ + 32 * 1024);
;         const bf16_t* vm_ = avTm + (size_t)(hd * 128 + vdv_) * 64 + vc_ * 8;
;         v0r[0] = *(const u32x4*)vm_; v0r[1] = *(const u32x4*)(vm_ + 64 * 64);
;     }
;     u32x4 k1r[2], v1r[2];
;     A_LOAD_REAL(k1r, v1r);
; #pragma unroll
;     for (int ks = 0; ks < 4; ++ks) asm volatile("" : "+v"(qf[ks]));
;     A_STORE(k0r, v0r, 0);
;     __syncthreads();
.LBB0_1809:
	s_or_b64 exec, exec, s[4:5]
	s_add_i32 s0, 0, 0x25000
	s_cmp_lg_u32 s0, -1
	s_cselect_b32 s0, s0, 0
	s_cselect_b32 s4, s57, 0
	s_waitcnt vmcnt(0)
	v_mov_b32_e32 v2, s0
	v_mov_b32_e32 v3, s4
	s_waitcnt lgkmcnt(0)
	s_barrier
	flat_load_dword v1, v[2:3] sc0 sc1
	s_waitcnt vmcnt(0) lgkmcnt(0)
	s_barrier
	v_readfirstlane_b32 s8, v1
	s_cmp_eq_u32 s8, -1
	s_cbranch_scc1 .LBB0_1823
	s_lshr_b32 s9, s8, 16
	s_and_b32 s0, s8, 0xffff
	s_cmp_gt_u32 s0, 7
	s_mov_b64 s[4:5], -1
	s_cbranch_scc0 .LBB0_1831
	s_add_i32 s4, s0, -8
	s_lshr_b32 s0, s4, 2
	s_and_b32 s0, s0, 0x3ffffffc
	s_and_b32 s5, s8, 3
	s_or_b32 s0, s0, s5
	v_mov_b32_e32 v132, v186
	s_sub_i32 s0, 31, s0
	s_lshl_b32 s6, s0, 7
	v_lshrrev_b32_e32 v1, 1, v132
	v_and_b32_e32 v146, 31, v132
	v_and_b32_e32 v148, 0x60, v1
	s_bfe_u32 s11, s4, 0x20002
	v_or3_b32 v138, v148, s6, v146
	s_lshl_b32 s54, s11, 12
	v_ashrrev_i32_e32 v139, 31, v138
	v_lshl_add_u64 v[2:3], v[138:139], 0, s[54:55]
	v_ashrrev_i32_e32 v147, 8, v132
	v_lshlrev_b64 v[136:137], 11, v[2:3]
	v_lshl_add_u64 v[2:3], s[68:69], 0, v[136:137]
	s_lshl_b32 s6, s9, 8
	s_mov_b32 s7, s55
	v_lshlrev_b32_e32 v4, 6, v147
	v_lshl_add_u64 v[2:3], v[2:3], 0, s[6:7]
	v_ashrrev_i32_e32 v5, 31, v4
	v_lshl_add_u64 v[2:3], v[4:5], 1, v[2:3]
	v_ashrrev_i32_e32 v4, 4, v132
	v_ashrrev_i32_e32 v5, 31, v4
	v_lshlrev_b64 v[12:13], 11, v[4:5]
	v_bfe_u32 v149, v132, 5, 1
	v_lshlrev_b32_e32 v1, 4, v132
	v_lshl_add_u64 v[12:13], s[64:65], 0, v[12:13]
	v_lshlrev_b32_e32 v98, 4, v149
	v_and_b32_e32 v140, 0xf0, v1
	v_mov_b32_e32 v141, v99
	v_lshl_add_u64 v[12:13], v[12:13], 0, s[6:7]
	v_lshl_add_u64 v[2:3], v[2:3], 0, v[98:99]
	v_lshl_add_u64 v[12:13], v[12:13], 0, v[140:141]
	global_load_dwordx4 v[100:103], v[2:3], off
	global_load_dwordx4 v[104:107], v[2:3], off offset:32
	global_load_dwordx4 v[108:111], v[2:3], off offset:64
	global_load_dwordx4 v[112:115], v[2:3], off offset:96
	global_load_dwordx4 v[116:119], v[12:13], off
	v_add_co_u32_e32 v2, vcc, s43, v12
	s_lshl_b32 s10, s9, 7
	v_ashrrev_i32_e32 v6, 3, v132
	v_addc_co_u32_e32 v3, vcc, 0, v13, vcc
	global_load_dwordx4 v[120:123], v[2:3], off
	v_add_u32_e32 v2, s10, v6
	v_ashrrev_i32_e32 v3, 31, v2
	v_lshlrev_b64 v[2:3], 7, v[2:3]
	v_and_b32_e32 v10, 0x70, v1
	v_mov_b32_e32 v11, v99
	v_lshl_add_u64 v[2:3], s[62:63], 0, v[2:3]
	v_lshl_add_u64 v[2:3], v[2:3], 0, v[10:11]
	global_load_dwordx4 v[124:127], v[2:3], off
	v_lshl_add_u64 v[8:9], v[4:5], 0, s[54:55]
	v_lshlrev_b64 v[8:9], 11, v[8:9]
	v_add_co_u32_e32 v2, vcc, s56, v2
	v_lshl_add_u64 v[8:9], s[44:45], 0, v[8:9]
	s_lshl_b32 s11, s11, 10
	v_addc_co_u32_e32 v3, vcc, 0, v3, vcc
	v_lshl_add_u64 v[8:9], v[8:9], 0, s[6:7]
	s_add_i32 s54, s11, s10
	v_ashrrev_i32_e32 v7, 31, v6
	global_load_dwordx4 v[128:131], v[2:3], off
	v_lshl_add_u64 v[82:83], v[8:9], 0, v[140:141]
	v_lshl_add_u64 v[8:9], v[6:7], 0, s[54:55]
	v_lshlrev_b64 v[8:9], 13, v[8:9]
	v_lshl_add_u64 v[8:9], s[60:61], 0, v[8:9]
	v_add_co_u32_e32 v2, vcc, s43, v82
	v_lshl_add_u64 v[84:85], v[8:9], 0, v[10:11]
	s_nop 0
	v_addc_co_u32_e32 v3, vcc, 0, v83, vcc
	v_add_co_u32_e32 v8, vcc, s74, v84
	global_load_dwordx4 v[74:77], v[82:83], off
	global_load_dwordx4 v[70:73], v[84:85], off
	v_addc_co_u32_e32 v9, vcc, 0, v85, vcc
	global_load_dwordx4 v[78:81], v[2:3], off
	global_load_dwordx4 v[66:69], v[8:9], off
	v_lshlrev_b32_e32 v2, 3, v132
	v_mul_lo_u32 v139, v4, s75
	v_add_u32_e32 v4, 0x200, v132
	v_and_b32_e32 v150, 0x60, v1
	v_and_b32_e32 v151, 8, v2
	v_lshrrev_b32_e32 v5, 4, v4
	v_add3_u32 v1, 0, v150, v151
	v_mul_lo_u32 v152, v6, s52
	v_add_u32_e32 v3, 0, v140
	v_mul_lo_u32 v141, v5, s75
	v_add_u32_e32 v97, v1, v152
	v_add_u32_e32 v87, v3, v139
	v_add_u32_e32 v96, v3, v141
	v_add_u32_e32 v2, 0x4000, v97
	s_waitcnt vmcnt(11)
	s_waitcnt vmcnt(10)
	s_waitcnt vmcnt(9)
	s_waitcnt vmcnt(8)
	s_waitcnt vmcnt(7)
	ds_write_b128 v87, v[116:119]
	v_mad_u32_u24 v42, v146, s75, 0
	v_lshl_or_b32 v154, v147, 7, v98
	s_waitcnt vmcnt(6)
	ds_write_b128 v96, v[120:123]
	s_waitcnt vmcnt(5)
	ds_write2_b64 v2, v[124:125], v[126:127] offset0:128 offset1:130
	v_lshrrev_b32_e32 v2, 3, v4
	v_mul_lo_u32 v153, v2, s52
	v_add_u32_e32 v155, v1, v153
	v_add_u32_e32 v1, 0x4000, v155
	s_waitcnt vmcnt(4)
	ds_write2_b64 v1, v[128:129], v[130:131] offset0:128 offset1:130
	v_add_u32_e32 v1, v42, v154
	s_waitcnt lgkmcnt(0)
	s_barrier
; DI void attn_s(const unsigned char* sK, int tt, int qb, int qs, int sub, int l31, int h,
;                const bf16x8 (&qf)[4], f32x16 (&O)[4], float& m, float& l, bf16x8 (&pb)[4]) {
;     ...
;         for (int i = 0; i < 4; ++i) st[i & 1] = MFMA32(ka[i], qf[i >> 1], st[i & 1]);
;         __builtin_amdgcn_sched_barrier(0);
; #pragma unroll
;         for (int i = 0; i < 4; ++i) st[i & 1] = MFMA32(kc[i], qf[2 + (i >> 1)], st[i & 1]);
;     }
;     if (tt == 0) {
; #pragma unroll
;         for (int i = 0; i < 16; ++i) { st[0][i] = -INFINITY; if (i < 8) st[1][i] = -INFINITY; }
;     } else if (tt >= 2 * qb + 1) {
;         const int kbase = (tt - 1) * 64 + 4 * h;
; #pragma unroll
;         for (int k2 = 0; k2 < 2; ++k2)
; #pragma unroll
;             for (int i = 0; i < 16; ++i) {
;                 const int key = kbase + k2 * 32 + (i & 3) + 8 * (i >> 2);
;                 if (key > qs) st[k2][i] = -INFINITY;
;             }
;     }
;     float mx;
;     {
;         float t[11];
; #pragma unroll
;         for (int i = 0; i < 5; ++i) t[i] = max3f(st[0][3 * i], st[0][3 * i + 1], st[0][3 * i + 2]);
; #pragma unroll
;         for (int i = 0; i < 5; ++i) t[5 + i] = max3f(st[1][3 * i], st[1][3 * i + 1], st[1][3 * i + 2]);
;         t[10] = fmaxf(st[0][15], st[1][15]);
;         const float u0 = max3f(t[0], t[1], t[2]), u1 = max3f(t[3], t[4], t[5]), u2 = max3f(t[6], t[7], t[8]);
;         mx = max3f(max3f(u0, u1, u2), t[9], t[10]);
;     }
;     mx = xor32_max(mx);
;     if (tt == 0 || __builtin_amdgcn_ballot_w64(mx > 8.0f) != 0ull) {
;         const float delta = tt == 0 ? mx : fmaxf(mx, 0.f);
;         const float alpha = __builtin_amdgcn_exp2f(-delta);
;         m += delta;
;         l *= alpha;
; #pragma unroll
;         for (int d = 0; d < 4; ++d) O[d] = O[d] * alpha;
; #pragma unroll
;         for (int k2 = 0; k2 < 2; ++k2) st[k2] = st[k2] - delta;
;     }
; #pragma unroll
;     for (int k2 = 0; k2 < 2; ++k2)
; #pragma unroll
;         for (int i = 0; i < 16; ++i) st[k2][i] = __builtin_amdgcn_exp2f(st[k2][i]);
;     {
;         const f32x16 sv = st[0] + st[1];
;         const float ps = (((sv[0] + sv[1]) + (sv[2] + sv[3])) + ((sv[4] + sv[5]) + (sv[6] + sv[7]))) + (((sv[8] + sv[9]) + (sv[10] + sv[11])) + ((sv[12] + sv[13]) + (sv[14] + sv[15])));
;         l += ps;
;     }
; #pragma unroll
;     for (int k4 = 0; k4 < 4; ++k4) {
	ds_read_b128 v[26:29], v1 offset:8704
	ds_read_b128 v[30:33], v1 offset:8736
	ds_read_b128 v[34:37], v1 offset:8768
	ds_read_b128 v[38:41], v1 offset:8800
	v_mov_b32_e32 v10, v0
	v_mov_b32_e32 v11, v0
	v_mov_b32_e32 v12, v0
	v_mov_b32_e32 v13, v0
	v_mov_b32_e32 v14, v0
	v_mov_b32_e32 v15, v0
	v_mov_b32_e32 v1, v0
	v_mov_b32_e32 v2, v0
	v_mov_b32_e32 v3, v0
	v_mov_b32_e32 v4, v0
	v_mov_b32_e32 v5, v0
	v_mov_b32_e32 v6, v0
	v_mov_b32_e32 v7, v0
	v_mov_b32_e32 v8, v0
	v_mov_b32_e32 v9, v0
	v_mov_b64_e32 v[24:25], v[14:15]
	v_mov_b64_e32 v[22:23], v[12:13]
	v_mov_b64_e32 v[20:21], v[10:11]
	v_mov_b64_e32 v[18:19], v[8:9]
	v_mov_b64_e32 v[16:17], v[6:7]
	v_mov_b64_e32 v[14:15], v[4:5]
	v_mov_b64_e32 v[12:13], v[2:3]
	v_mov_b64_e32 v[10:11], v[0:1]
	s_waitcnt lgkmcnt(3)
	s_nop 0
	v_mfma_f32_32x32x16_bf16 v[10:25], v[26:29], v[100:103], v[10:25]
	s_waitcnt lgkmcnt(2)
	v_mfma_f32_32x32x16_bf16 v[10:25], v[30:33], v[104:107], v[10:25]
	s_waitcnt lgkmcnt(1)
	v_mfma_f32_32x32x16_bf16 v[10:25], v[34:37], v[108:111], v[10:25]
	v_max3_f32 v1, v188, v188, v188
	s_nop 0
	v_max3_f32 v2, v1, v1, v1
	s_waitcnt lgkmcnt(0)
	v_mfma_f32_32x32x16_bf16 v[10:25], v[38:41], v[112:115], v[10:25]
	v_max3_f32 v3, v188, v188, v18
	v_max3_f32 v4, v19, v20, v21
	v_max3_f32 v5, v22, v23, v24
	s_nop 0
	v_max3_f32 v1, v1, v3, v4
	s_nop 10
	v_max_f32_e32 v6, v25, v25
	v_max3_f32 v1, v2, v2, v1
	v_max_f32_e32 v6, 0xff800000, v6
	v_max3_f32 v1, v1, v5, v6
	s_nop 0
	v_mov_b32_e32 v2, v1
	s_nop 1
	v_permlane32_swap_b32_e32 v1, v2
	v_max_f32_e32 v2, v2, v2
	v_max_f32_e32 v1, v1, v1
	v_max_f32_e32 v86, v1, v2
	v_sub_f32_e32 v1, 0xff800000, v86
	v_sub_f32_e32 v19, v19, v86
	v_sub_f32_e32 v26, v18, v86
	v_sub_f32_e32 v21, v21, v86
	v_sub_f32_e32 v20, v20, v86
	v_exp_f32_e32 v18, v1
	v_exp_f32_e32 v26, v26
	v_exp_f32_e32 v27, v19
	v_sub_f32_e32 v23, v23, v86
	v_sub_f32_e32 v22, v22, v86
	v_exp_f32_e32 v28, v20
	v_exp_f32_e32 v29, v21
	v_sub_f32_e32 v25, v25, v86
	v_sub_f32_e32 v24, v24, v86
	v_exp_f32_e32 v30, v22
	v_exp_f32_e32 v31, v23
	v_exp_f32_e32 v32, v24
	v_exp_f32_e32 v33, v25
	v_pk_add_f32 v[34:35], v[18:19], v[26:27] op_sel_hi:[0,1]
	v_add_f32_e32 v36, v18, v18
	v_pk_add_f32 v[24:25], v[18:19], v[28:29] op_sel_hi:[0,1]
	v_mov_b32_e32 v37, v34
	v_mov_b32_e32 v34, v36
	v_pk_add_f32 v[22:23], v[18:19], v[30:31] op_sel_hi:[0,1]
	v_pk_add_f32 v[34:35], v[36:37], v[34:35]
	v_mov_b32_e32 v37, v24
	v_mov_b32_e32 v24, v36
	v_pk_add_f32 v[20:21], v[18:19], v[32:33] op_sel_hi:[0,1]
	v_pk_add_f32 v[24:25], v[36:37], v[24:25]
	v_mov_b32_e32 v37, v22
	v_mov_b32_e32 v22, v36
	v_pk_add_f32 v[22:23], v[36:37], v[22:23]
	v_mov_b32_e32 v37, v20
	v_mov_b32_e32 v20, v36
	v_pk_add_f32 v[20:21], v[36:37], v[20:21]
	v_cvt_pk_bf16_f32 v88, v18, v18
	v_lshlrev_b32_e32 v18, 7, v146
	v_pk_add_f32 v[24:25], v[34:35], v[24:25]
	v_pk_add_f32 v[20:21], v[22:23], v[20:21]
	v_sub_u32_e32 v18, v42, v18
	v_pk_add_f32 v[20:21], v[24:25], v[20:21]
	v_add_u32_e32 v185, v18, v98
	v_add_f32_e32 v1, v20, v21
	ds_read_b128 v[18:21], v185 offset:17408
	ds_read_b128 v[22:25], v185 offset:22016
	ds_read_b128 v[92:95], v185 offset:26624
	ds_read_b128 v[142:145], v185 offset:31232
	v_exp_f32_e64 v184, -v86
	v_mov_b32_e32 v89, v88
	v_mov_b32_e32 v90, v88
	v_mov_b32_e32 v91, v88
	v_mul_f32_e32 v2, 0, v184
	v_mov_b32_e32 v3, v2
	v_mov_b32_e32 v4, v2
	v_mov_b32_e32 v5, v2
	v_mov_b32_e32 v6, v2
	v_mov_b32_e32 v7, v2
	v_mov_b32_e32 v8, v2
	v_mov_b32_e32 v9, v2
	v_mov_b32_e32 v10, v2
	v_mov_b32_e32 v11, v2
	v_mov_b32_e32 v12, v2
	v_mov_b32_e32 v13, v2
	v_mov_b32_e32 v14, v2
	v_mov_b32_e32 v15, v2
	v_mov_b32_e32 v16, v2
	v_mov_b32_e32 v17, v2
	v_cvt_pk_bf16_f32 v156, v26, v27
	v_cvt_pk_bf16_f32 v157, v28, v29
	v_cvt_pk_bf16_f32 v158, v30, v31
	v_cvt_pk_bf16_f32 v159, v32, v33
	ds_read_b128 v[160:163], v185 offset:17440
	ds_read_b128 v[164:167], v185 offset:22048
	ds_read_b128 v[168:171], v185 offset:26656
	ds_read_b128 v[172:175], v185 offset:31264
	s_waitcnt lgkmcnt(7)
	v_mfma_f32_32x32x16_bf16 v[50:65], v[18:21], v[88:91], v[2:17]
	s_waitcnt lgkmcnt(6)
	v_mfma_f32_32x32x16_bf16 v[34:49], v[22:25], v[88:91], v[2:17]
	s_waitcnt lgkmcnt(5)
	v_mfma_f32_32x32x16_bf16 v[18:33], v[92:95], v[88:91], v[2:17]
	s_waitcnt lgkmcnt(4)
	v_mfma_f32_32x32x16_bf16 v[2:17], v[142:145], v[88:91], v[2:17]
	ds_read_b128 v[92:95], v185 offset:17472
	ds_read_b128 v[142:145], v185 offset:22080
	ds_read_b128 v[176:179], v185 offset:26688
	ds_read_b128 v[180:183], v185 offset:31296
	s_waitcnt lgkmcnt(7)
	v_mfma_f32_32x32x16_bf16 v[50:65], v[160:163], v[88:91], v[50:65]
	s_waitcnt lgkmcnt(6)
	v_mfma_f32_32x32x16_bf16 v[34:49], v[164:167], v[88:91], v[34:49]
	s_waitcnt lgkmcnt(5)
	v_mfma_f32_32x32x16_bf16 v[18:33], v[168:171], v[88:91], v[18:33]
	s_waitcnt lgkmcnt(4)
	v_mfma_f32_32x32x16_bf16 v[2:17], v[172:175], v[88:91], v[2:17]
	ds_read_b128 v[160:163], v185 offset:17504
	ds_read_b128 v[164:167], v185 offset:22112
	ds_read_b128 v[168:171], v185 offset:26720
	ds_read_b128 v[172:175], v185 offset:31328
	s_waitcnt lgkmcnt(7)
	v_mfma_f32_32x32x16_bf16 v[50:65], v[92:95], v[88:91], v[50:65]
	s_waitcnt lgkmcnt(6)
	v_mfma_f32_32x32x16_bf16 v[34:49], v[142:145], v[88:91], v[34:49]
	s_waitcnt lgkmcnt(5)
	v_mfma_f32_32x32x16_bf16 v[18:33], v[176:179], v[88:91], v[18:33]
	s_waitcnt lgkmcnt(4)
	v_mfma_f32_32x32x16_bf16 v[2:17], v[180:183], v[88:91], v[2:17]
	s_waitcnt lgkmcnt(3)
	v_mfma_f32_32x32x16_bf16 v[50:65], v[160:163], v[156:159], v[50:65]
	s_waitcnt vmcnt(3)
	ds_write_b128 v87, v[74:77] offset:35840
	s_waitcnt vmcnt(1)
	ds_write_b128 v96, v[78:81] offset:35840
	v_add_u32_e32 v74, 0xd000, v97
	ds_write2_b64 v74, v[70:71], v[72:73] offset1:2
	v_add_u32_e32 v70, 0xd000, v155
	v_fmac_f32_e32 v1, 0, v184
	s_cmpk_gt_u32 s4, 0x7f
	s_waitcnt vmcnt(0)
	ds_write2_b64 v70, v[66:67], v[68:69] offset1:2
	s_waitcnt lgkmcnt(6)
	v_mfma_f32_32x32x16_bf16 v[34:49], v[164:167], v[156:159], v[34:49]
	s_waitcnt lgkmcnt(0)
	s_barrier
; #define MFMA32(a, b, c) __builtin_amdgcn_mfma_f32_32x32x16_bf16((a), (b), (c), 0, 0, 0)
; DI void attn_s(const unsigned char* sK, int tt, int qb, int qs, int sub, int l31, int h,
;                const bf16x8 (&qf)[4], f32x16 (&O)[4], float& m, float& l, bf16x8 (&pb)[4]) {
;     ...
;     for (int k2 = 0; k2 < 2; ++k2)
; #pragma unroll
;         for (int i = 0; i < 16; ++i) st[k2][i] = -m;
;     {
;         const unsigned char* kb = sK + l31 * A_KROWB + (sub * 64 + 8 * h) * 2;
;         bf16x8 ka[4], kc[4];
; #pragma unroll
;         for (int i = 0; i < 4; ++i) ka[i] = *(const bf16x8*)(kb + (i & 1) * 32 * A_KROWB + (i >> 1) * 32);
;         __builtin_amdgcn_sched_barrier(0);
; #pragma unroll
;         for (int i = 0; i < 4; ++i) kc[i] = *(const bf16x8*)(kb + (i & 1) * 32 * A_KROWB + (2 + (i >> 1)) * 32);
;         __builtin_amdgcn_sched_barrier(0);
; #pragma unroll
;         for (int i = 0; i < 4; ++i) st[i & 1] = MFMA32(ka[i], qf[i >> 1], st[i & 1]);
;         __builtin_amdgcn_sched_barrier(0);
; #pragma unroll
;         for (int i = 0; i < 4; ++i) st[i & 1] = MFMA32(kc[i], qf[2 + (i >> 1)], st[i & 1]);
	v_mfma_f32_32x32x16_bf16 v[18:33], v[168:171], v[156:159], v[18:33]
	v_mfma_f32_32x32x16_bf16 v[2:17], v[172:175], v[156:159], v[2:17]
	s_cbranch_scc1 .LBB0_1824
	s_lshr_b32 s4, s4, 1
	s_lshl_b32 s5, s5, 1
	s_and_b32 s4, s4, 0x7ffffff8
	s_lshl_b32 s0, s0, 1
	s_or_b32 s4, s5, s4
	v_mul_u32_u24_e32 v155, 0x110, v146
	v_mul_u32_u24_e32 v156, 0x90, v146
	s_mov_b32 s13, 1
	s_add_i32 s6, s0, 3
	v_lshl_add_u64 v[142:143], v[84:85], 0, s[88:89]
	v_lshl_add_u64 v[142:143], v[142:143], 0, s[88:89]
	v_add_f32_e32 v157, 0, v86
	v_lshl_add_u64 v[144:145], v[82:83], 0, s[90:91]
	v_lshl_add_u64 v[144:145], v[144:145], 0, s[90:91]
	s_mov_b32 s7, 2
	v_lshl_or_b32 v158, v149, 2, 59
	s_sub_i32 s11, 0, s4
	s_movk_i32 s12, 0xffc0
	v_xor_b32_e32 v240, 0x80000000, v157
	v_mov_b32_e32 v241, v240
	v_mov_b32_e32 v242, v240
	v_mov_b32_e32 v243, v240
	v_mov_b32_e32 v244, v240
	v_mov_b32_e32 v245, v240
	v_mov_b32_e32 v246, v240
	v_mov_b32_e32 v247, v240
	v_mov_b32_e32 v248, v240
	v_mov_b32_e32 v249, v240
	v_mov_b32_e32 v250, v240
	v_mov_b32_e32 v251, v240
	v_mov_b32_e32 v252, v240
	v_mov_b32_e32 v253, v240
	v_mov_b32_e32 v254, v240
	v_mov_b32_e32 v255, v240
	v_readfirstlane_b32 s99, v147
	s_cmp_eq_u32 s99, 1
	s_cbranch_scc0 .Lpipe_nooffs
	s_barrier
.Lpipe_nooffs:
	s_barrier
	v_lshl_add_u64 v[184:185], v[82:83], 0, s[90:91]
	global_load_dwordx4 v[116:119], v[184:185], off
	s_nop 0
	v_lshl_add_u64 v[184:185], v[184:185], 0, s[92:93]
	global_load_dwordx4 v[120:123], v[184:185], off
	s_nop 0
	v_lshl_add_u64 v[184:185], v[84:85], 0, s[88:89]
	global_load_dwordx4 v[124:127], v[184:185], off
	s_nop 0
	v_add_co_u32_e32 v184, vcc, 0x80000, v184
	s_nop 1
	v_addc_co_u32_e32 v185, vcc, 0, v185, vcc
	global_load_dwordx4 v[128:131], v[184:185], off
	s_mul_i32 s98, s13, 0x8c00
	s_add_i32 s98, s98, 0
	v_add3_u32 v67, s98, v155, v154
	ds_read_b128 v[160:163], v67
	ds_read_b128 v[164:167], v67 offset:32
	ds_read_b128 v[168:171], v67 offset:8704
	ds_read_b128 v[172:175], v67 offset:8736
	ds_read_b128 v[176:179], v67 offset:64
	ds_read_b128 v[180:183], v67 offset:96
	ds_read_b128 v[192:195], v67 offset:8768
	ds_read_b128 v[196:199], v67 offset:8800
	s_waitcnt lgkmcnt(7)
	s_nop 0
	v_mfma_f32_32x32x16_bf16 v[82:97], v[160:163], v[100:103], v[240:255]
	s_waitcnt lgkmcnt(5)
	v_mfma_f32_32x32x16_bf16 v[66:81], v[168:171], v[100:103], v[240:255]
	v_mfma_f32_32x32x16_bf16 v[82:97], v[164:167], v[104:107], v[82:97]
	s_waitcnt lgkmcnt(4)
	v_mfma_f32_32x32x16_bf16 v[66:81], v[172:175], v[104:107], v[66:81]
	s_waitcnt lgkmcnt(3)
	v_mfma_f32_32x32x16_bf16 v[82:97], v[176:179], v[108:111], v[82:97]
	s_waitcnt lgkmcnt(1)
	v_mfma_f32_32x32x16_bf16 v[66:81], v[192:195], v[108:111], v[66:81]
	v_mfma_f32_32x32x16_bf16 v[82:97], v[180:183], v[112:115], v[82:97]
	s_waitcnt lgkmcnt(0)
	v_mfma_f32_32x32x16_bf16 v[66:81], v[196:199], v[112:115], v[66:81]
	s_add_i32 s14, s12, 0x42
	s_cmp_ge_i32 s14, s6
	s_cbranch_scc1 .Lpipe_nostage_p
	s_mul_i32 s4, s7, 0x8c00
	s_add_i32 s4, s4, 0
	v_add_u32_e32 v184, s4, v140
	v_add_u32_e32 v185, v184, v139
	v_add_u32_e32 v184, v184, v141
	s_waitcnt vmcnt(3)
	ds_write_b128 v185, v[116:119]
	s_waitcnt vmcnt(2)
	ds_write_b128 v184, v[120:123]
	v_add3_u32 v184, s4, v150, v151
	v_add_u32_e32 v185, v184, v152
	v_add_u32_e32 v184, v184, v153
	v_add_u32_e32 v185, 0x4000, v185
	v_add_u32_e32 v184, 0x4000, v184
	s_waitcnt vmcnt(1)
	ds_write2_b64 v185, v[124:125], v[126:127] offset0:128 offset1:130
	s_waitcnt vmcnt(0)
	ds_write2_b64 v184, v[128:129], v[130:131] offset0:128 offset1:130
	s_add_i32 s14, s12, 0x43
	s_cmp_ge_i32 s14, s6
	s_cbranch_scc1 .Lpipe_nostage_p
	v_add_co_u32_e32 v184, vcc, 0x10000, v144
	global_load_dwordx4 v[116:119], v[144:145], off
	s_nop 0
	v_addc_co_u32_e32 v185, vcc, 0, v145, vcc
	global_load_dwordx4 v[120:123], v[184:185], off
	global_load_dwordx4 v[124:127], v[142:143], off
	v_add_co_u32_e32 v184, vcc, 0x80000, v142
	v_lshl_add_u64 v[144:145], v[144:145], 0, s[90:91]
	s_nop 0
	v_addc_co_u32_e32 v185, vcc, 0, v143, vcc
	global_load_dwordx4 v[128:131], v[184:185], off
	v_lshl_add_u64 v[142:143], v[142:143], 0, s[88:89]

; DI float xor32_max(float x) { auto r = __builtin_amdgcn_permlane32_swap(__float_as_uint(x), __float_as_uint(x), false, false); return fmaxf(__uint_as_float(r[0]), __uint_as_float(r[1])); }
; DI float max3f(float a, float b, float c) { float r; asm("v_max3_f32 %0, %1, %2, %3" : "=v"(r) : "v"(a), "v"(b), "v"(c)); return r; }
; DI void attn_s(const unsigned char* sK, int tt, int qb, int qs, int sub, int l31, int h,
;                const bf16x8 (&qf)[4], f32x16 (&O)[4], float& m, float& l, bf16x8 (&pb)[4]) {
;     ...
;     } else if (tt >= 2 * qb + 1) {
;         const int kbase = (tt - 1) * 64 + 4 * h;
; #pragma unroll
;         for (int k2 = 0; k2 < 2; ++k2)
; #pragma unroll
;             for (int i = 0; i < 16; ++i) {
;                 const int key = kbase + k2 * 32 + (i & 3) + 8 * (i >> 2);
;                 if (key > qs) st[k2][i] = -INFINITY;
;             }
;     }
;     float mx;
;     {
;         float t[11];
; #pragma unroll
;         for (int i = 0; i < 5; ++i) t[i] = max3f(st[0][3 * i], st[0][3 * i + 1], st[0][3 * i + 2]);
; #pragma unroll
;         for (int i = 0; i < 5; ++i) t[5 + i] = max3f(st[1][3 * i], st[1][3 * i + 1], st[1][3 * i + 2]);
;         t[10] = fmaxf(st[0][15], st[1][15]);
;         const float u0 = max3f(t[0], t[1], t[2]), u1 = max3f(t[3], t[4], t[5]), u2 = max3f(t[6], t[7], t[8]);
;         mx = max3f(max3f(u0, u1, u2), t[9], t[10]);
;     }
;     mx = xor32_max(mx);
;     if (tt == 0 || __builtin_amdgcn_ballot_w64(mx > 8.0f) != 0ull) {
.Lpipe_loop:
	v_add3_u32 v191, s98, v156, v98
	ds_read_b128 v[172:175], v191 offset:17408
	ds_read_b128 v[176:179], v191 offset:22016
	ds_read_b128 v[180:183], v191 offset:26624
	ds_read_b128 v[192:195], v191 offset:31232
	ds_read_b128 v[200:203], v191 offset:17440
	ds_read_b128 v[204:207], v191 offset:22048
	ds_read_b128 v[208:211], v191 offset:26656
	ds_read_b128 v[212:215], v191 offset:31264
	s_add_i32 s14, s12, 0x41
	s_cmp_le_i32 s14, s0
	s_cbranch_scc1 .Lpipe_nomask_l
	v_subrev_u32_e32 v159, 59, v158
	v_cmp_gt_i32_e32 vcc, v159, v138
	s_nop 1
	v_cndmask_b32_e32 v160, v82, v188, vcc
	v_cmp_lt_i32_e32 vcc, v159, v138
	v_subrev_u32_e32 v159, 57, v158
	s_nop 0
	v_cndmask_b32_e32 v82, v160, v82, vcc
	v_cndmask_b32_e32 v83, v188, v83, vcc
	v_cmp_le_i32_e32 vcc, v159, v138
	v_subrev_u32_e32 v159, 56, v158
	s_nop 0
	v_cndmask_b32_e32 v84, v188, v84, vcc
	v_cmp_le_i32_e32 vcc, v159, v138
	v_subrev_u32_e32 v159, 51, v158
	s_nop 0
	v_cndmask_b32_e32 v85, v188, v85, vcc
	v_cmp_le_i32_e32 vcc, v159, v138
	v_subrev_u32_e32 v159, 50, v158
	s_nop 0
	v_cndmask_b32_e32 v86, v188, v86, vcc
	v_cmp_le_i32_e32 vcc, v159, v138
	v_subrev_u32_e32 v159, 49, v158
	s_nop 0
	v_cndmask_b32_e32 v87, v188, v87, vcc
	v_cmp_le_i32_e32 vcc, v159, v138
	v_subrev_u32_e32 v159, 48, v158
	s_nop 0
	v_cndmask_b32_e32 v88, v188, v88, vcc
	v_cmp_le_i32_e32 vcc, v159, v138
	v_subrev_u32_e32 v159, 43, v158
	s_nop 0
	v_cndmask_b32_e32 v89, v188, v89, vcc
	v_cmp_le_i32_e32 vcc, v159, v138
	v_subrev_u32_e32 v159, 42, v158
	s_nop 0
	v_cndmask_b32_e32 v90, v188, v90, vcc
	v_cmp_le_i32_e32 vcc, v159, v138
	v_subrev_u32_e32 v159, 41, v158
	s_nop 0
	v_cndmask_b32_e32 v91, v188, v91, vcc
	v_cmp_le_i32_e32 vcc, v159, v138
	v_subrev_u32_e32 v159, 40, v158
	s_nop 0
	v_cndmask_b32_e32 v92, v188, v92, vcc
	v_cmp_le_i32_e32 vcc, v159, v138
	v_subrev_u32_e32 v159, 35, v158
	s_nop 0
	v_cndmask_b32_e32 v93, v188, v93, vcc
	v_cmp_le_i32_e32 vcc, v159, v138
	v_subrev_u32_e32 v159, 34, v158
	s_nop 0
	v_cndmask_b32_e32 v94, v188, v94, vcc
	v_cmp_le_i32_e32 vcc, v159, v138
	v_subrev_u32_e32 v159, 33, v158
	s_nop 0
	v_cndmask_b32_e32 v95, v188, v95, vcc
	v_cmp_le_i32_e32 vcc, v159, v138
	v_subrev_u32_e32 v159, 32, v158
	s_nop 0
	v_cndmask_b32_e32 v96, v188, v96, vcc
	v_cmp_le_i32_e32 vcc, v159, v138
	v_subrev_u32_e32 v159, 27, v158
	s_nop 0
	v_cndmask_b32_e32 v97, v188, v97, vcc
	v_cmp_le_i32_e32 vcc, v159, v138
	v_subrev_u32_e32 v159, 26, v158
	s_nop 0
	v_cndmask_b32_e32 v66, v188, v66, vcc
	v_cmp_le_i32_e32 vcc, v159, v138
	v_subrev_u32_e32 v159, 25, v158
	s_nop 0
	v_cndmask_b32_e32 v67, v188, v67, vcc
	v_cmp_le_i32_e32 vcc, v159, v138
	v_subrev_u32_e32 v159, 24, v158
	s_nop 0
	v_cndmask_b32_e32 v68, v188, v68, vcc
	v_cmp_le_i32_e32 vcc, v159, v138
	v_subrev_u32_e32 v159, 19, v158
	s_nop 0
	v_cndmask_b32_e32 v69, v188, v69, vcc
	v_cmp_le_i32_e32 vcc, v159, v138
	v_subrev_u32_e32 v159, 18, v158
	s_nop 0
	v_cndmask_b32_e32 v70, v188, v70, vcc
	v_cmp_le_i32_e32 vcc, v159, v138
	v_subrev_u32_e32 v159, 17, v158
	s_nop 0
	v_cndmask_b32_e32 v71, v188, v71, vcc
	v_cmp_le_i32_e32 vcc, v159, v138
	v_add_u32_e32 v159, -16, v158
	s_nop 0
	v_cndmask_b32_e32 v72, v188, v72, vcc
	v_cmp_le_i32_e32 vcc, v159, v138
	v_add_u32_e32 v159, -11, v158
	s_nop 0
	v_cndmask_b32_e32 v73, v188, v73, vcc
	v_cmp_le_i32_e32 vcc, v159, v138
	v_add_u32_e32 v159, -10, v158
	s_nop 0
	v_cndmask_b32_e32 v74, v188, v74, vcc
	v_cmp_le_i32_e32 vcc, v159, v138
	v_add_u32_e32 v159, -9, v158
	s_nop 0
	v_cndmask_b32_e32 v75, v188, v75, vcc
	v_cmp_le_i32_e32 vcc, v159, v138
	v_add_u32_e32 v159, -8, v158
	s_nop 0
	v_cndmask_b32_e32 v76, v188, v76, vcc
	v_cmp_le_i32_e32 vcc, v159, v138
	v_add_u32_e32 v159, -3, v158
	s_nop 0
	v_cndmask_b32_e32 v77, v188, v77, vcc
	v_cmp_le_i32_e32 vcc, v159, v138
	v_add_u32_e32 v159, -2, v158
	s_nop 0
	v_cndmask_b32_e32 v78, v188, v78, vcc
	v_cmp_le_i32_e32 vcc, v159, v138
	v_add_u32_e32 v159, -1, v158
	s_nop 0
	v_cndmask_b32_e32 v79, v188, v79, vcc
	v_cmp_le_i32_e32 vcc, v159, v138
	s_nop 1
	v_cndmask_b32_e32 v80, v188, v80, vcc
	v_cmp_le_i32_e32 vcc, v158, v138
	s_nop 1
	v_cndmask_b32_e32 v81, v188, v81, vcc
.Lpipe_nomask_l:
	v_max3_f32 v159, v82, v83, v84
	v_max3_f32 v160, v85, v86, v87
	v_max3_f32 v161, v88, v89, v90
	v_max3_f32 v162, v91, v92, v93
	v_max3_f32 v163, v94, v95, v96
	v_max3_f32 v164, v66, v67, v68
	v_max3_f32 v165, v69, v70, v71
	v_max3_f32 v166, v72, v73, v74
	v_max3_f32 v159, v159, v160, v161
	v_max3_f32 v167, v75, v76, v77
	v_max_f32_e32 v169, v81, v81
	v_max_f32_e32 v170, v97, v97
	v_max3_f32 v160, v162, v163, v164
	v_max3_f32 v161, v165, v166, v167
	v_max3_f32 v168, v78, v79, v80
	v_max_f32_e32 v169, v170, v169
	v_max3_f32 v159, v159, v160, v161
	s_mov_b32 s14, 0x41000000
	v_max3_f32 v159, v159, v168, v169
	v_mov_b32_e32 v160, v159
	s_nop 1
	v_permlane32_swap_b32_e32 v159, v160
	v_max_f32_e32 v160, v160, v160
	v_max_f32_e32 v159, v159, v159
	v_max_f32_e32 v159, v159, v160
	v_cmp_lt_f32_e32 vcc, s14, v159
	s_cbranch_vccz .Lpipe_norescale_l
; DI void attn_s(const unsigned char* sK, int tt, int qb, int qs, int sub, int l31, int h,
;                const bf16x8 (&qf)[4], f32x16 (&O)[4], float& m, float& l, bf16x8 (&pb)[4]) {
;     ...
;     if (tt == 0 || __builtin_amdgcn_ballot_w64(mx > 8.0f) != 0ull) {
;         const float delta = tt == 0 ? mx : fmaxf(mx, 0.f);
;         const float alpha = __builtin_amdgcn_exp2f(-delta);
;         m += delta;
;         l *= alpha;
; #pragma unroll
;         for (int d = 0; d < 4; ++d) O[d] = O[d] * alpha;
; #pragma unroll
;         for (int k2 = 0; k2 < 2; ++k2) st[k2] = st[k2] - delta;
;     }
	v_max_f32_e32 v159, v159, v159
	v_max_f32_e32 v159, 0, v159
	v_exp_f32_e64 v160, -v159
	v_add_f32_e32 v157, v157, v159
	v_xor_b32_e32 v240, 0x80000000, v157
	v_mov_b32_e32 v241, v240
	v_mov_b32_e32 v242, v240
	v_mov_b32_e32 v243, v240
	v_mov_b32_e32 v244, v240
	v_mov_b32_e32 v245, v240
	v_mov_b32_e32 v246, v240
	v_mov_b32_e32 v247, v240
	v_mov_b32_e32 v248, v240
	v_mov_b32_e32 v249, v240
	v_mov_b32_e32 v250, v240
	v_mov_b32_e32 v251, v240
	v_mov_b32_e32 v252, v240
	v_mov_b32_e32 v253, v240
	v_mov_b32_e32 v254, v240
	v_mov_b32_e32 v255, v240
	v_sub_f32_e32 v97, v97, v159
	v_sub_f32_e32 v82, v82, v159
	v_mul_f32_e32 v1, v1, v160
	v_pk_mul_f32 v[64:65], v[64:65], v[160:161] op_sel_hi:[1,0]
	v_pk_mul_f32 v[62:63], v[62:63], v[160:161] op_sel_hi:[1,0]
	v_pk_mul_f32 v[60:61], v[60:61], v[160:161] op_sel_hi:[1,0]
	v_pk_mul_f32 v[58:59], v[58:59], v[160:161] op_sel_hi:[1,0]
	v_pk_mul_f32 v[56:57], v[56:57], v[160:161] op_sel_hi:[1,0]
	v_pk_mul_f32 v[54:55], v[54:55], v[160:161] op_sel_hi:[1,0]
	v_pk_mul_f32 v[52:53], v[52:53], v[160:161] op_sel_hi:[1,0]
	v_pk_mul_f32 v[50:51], v[50:51], v[160:161] op_sel_hi:[1,0]
	v_pk_mul_f32 v[48:49], v[48:49], v[160:161] op_sel_hi:[1,0]
	v_pk_mul_f32 v[46:47], v[46:47], v[160:161] op_sel_hi:[1,0]
	v_pk_mul_f32 v[44:45], v[44:45], v[160:161] op_sel_hi:[1,0]
	v_pk_mul_f32 v[42:43], v[42:43], v[160:161] op_sel_hi:[1,0]
	v_pk_mul_f32 v[40:41], v[40:41], v[160:161] op_sel_hi:[1,0]
	v_pk_mul_f32 v[38:39], v[38:39], v[160:161] op_sel_hi:[1,0]
	v_pk_mul_f32 v[36:37], v[36:37], v[160:161] op_sel_hi:[1,0]
	v_pk_mul_f32 v[34:35], v[34:35], v[160:161] op_sel_hi:[1,0]
	v_pk_mul_f32 v[32:33], v[32:33], v[160:161] op_sel_hi:[1,0]
	v_pk_mul_f32 v[30:31], v[30:31], v[160:161] op_sel_hi:[1,0]
	v_pk_mul_f32 v[28:29], v[28:29], v[160:161] op_sel_hi:[1,0]
	v_pk_mul_f32 v[26:27], v[26:27], v[160:161] op_sel_hi:[1,0]
	v_pk_mul_f32 v[24:25], v[24:25], v[160:161] op_sel_hi:[1,0]
	v_pk_mul_f32 v[22:23], v[22:23], v[160:161] op_sel_hi:[1,0]
	v_pk_mul_f32 v[20:21], v[20:21], v[160:161] op_sel_hi:[1,0]
	v_pk_mul_f32 v[18:19], v[18:19], v[160:161] op_sel_hi:[1,0]
	v_pk_mul_f32 v[16:17], v[16:17], v[160:161] op_sel_hi:[1,0]
	v_pk_mul_f32 v[14:15], v[14:15], v[160:161] op_sel_hi:[1,0]
	v_pk_mul_f32 v[12:13], v[12:13], v[160:161] op_sel_hi:[1,0]
	v_pk_mul_f32 v[10:11], v[10:11], v[160:161] op_sel_hi:[1,0]
	v_pk_mul_f32 v[8:9], v[8:9], v[160:161] op_sel_hi:[1,0]
	v_pk_mul_f32 v[6:7], v[6:7], v[160:161] op_sel_hi:[1,0]
	v_pk_mul_f32 v[4:5], v[4:5], v[160:161] op_sel_hi:[1,0]
	v_pk_mul_f32 v[2:3], v[2:3], v[160:161] op_sel_hi:[1,0]
	v_sub_f32_e32 v83, v83, v159
	v_sub_f32_e32 v84, v84, v159
	v_sub_f32_e32 v85, v85, v159
	v_sub_f32_e32 v86, v86, v159
	v_sub_f32_e32 v87, v87, v159
	v_sub_f32_e32 v88, v88, v159
	v_sub_f32_e32 v89, v89, v159
	v_sub_f32_e32 v90, v90, v159
	v_sub_f32_e32 v91, v91, v159
	v_sub_f32_e32 v92, v92, v159
	v_sub_f32_e32 v93, v93, v159
	v_sub_f32_e32 v94, v94, v159
	v_sub_f32_e32 v95, v95, v159
	v_sub_f32_e32 v96, v96, v159
	v_sub_f32_e32 v66, v66, v159
	v_sub_f32_e32 v67, v67, v159
	v_sub_f32_e32 v68, v68, v159
	v_sub_f32_e32 v69, v69, v159
	v_sub_f32_e32 v70, v70, v159
	v_sub_f32_e32 v71, v71, v159
	v_sub_f32_e32 v72, v72, v159
	v_sub_f32_e32 v73, v73, v159
	v_sub_f32_e32 v74, v74, v159
	v_sub_f32_e32 v75, v75, v159
	v_sub_f32_e32 v76, v76, v159
	v_sub_f32_e32 v77, v77, v159
	v_sub_f32_e32 v78, v78, v159
	v_sub_f32_e32 v79, v79, v159
	v_sub_f32_e32 v80, v80, v159
	v_sub_f32_e32 v81, v81, v159
; #define MFMA32(a, b, c) __builtin_amdgcn_mfma_f32_32x32x16_bf16((a), (b), (c), 0, 0, 0)
; DI unsigned pk2(float a, float b) { f32x2 v = {a, b}; return __builtin_bit_cast(unsigned, __builtin_convertvector(v, bfv2)); }
; DI void attn_s(const unsigned char* sK, int tt, int qb, int qs, int sub, int l31, int h,
;                const bf16x8 (&qf)[4], f32x16 (&O)[4], float& m, float& l, bf16x8 (&pb)[4]) {
;     ...
;     for (int k2 = 0; k2 < 2; ++k2)
; #pragma unroll
;         for (int i = 0; i < 16; ++i) st[k2][i] = -m;
;     {
;         const unsigned char* kb = sK + l31 * A_KROWB + (sub * 64 + 8 * h) * 2;
;         bf16x8 ka[4], kc[4];
; #pragma unroll
;         for (int i = 0; i < 4; ++i) ka[i] = *(const bf16x8*)(kb + (i & 1) * 32 * A_KROWB + (i >> 1) * 32);
;         __builtin_amdgcn_sched_barrier(0);
; #pragma unroll
;         for (int i = 0; i < 4; ++i) kc[i] = *(const bf16x8*)(kb + (i & 1) * 32 * A_KROWB + (2 + (i >> 1)) * 32);
;         __builtin_amdgcn_sched_barrier(0);
; #pragma unroll
;         for (int i = 0; i < 4; ++i) st[i & 1] = MFMA32(ka[i], qf[i >> 1], st[i & 1]);
;         __builtin_amdgcn_sched_barrier(0);
; #pragma unroll
;         for (int i = 0; i < 4; ++i) st[i & 1] = MFMA32(kc[i], qf[2 + (i >> 1)], st[i & 1]);
;     ...
; #pragma unroll
;     for (int k2 = 0; k2 < 2; ++k2)
; #pragma unroll
;         for (int i = 0; i < 16; ++i) st[k2][i] = __builtin_amdgcn_exp2f(st[k2][i]);
;     {
;         const f32x16 sv = st[0] + st[1];
;         const float ps = (((sv[0] + sv[1]) + (sv[2] + sv[3])) + ((sv[4] + sv[5]) + (sv[6] + sv[7]))) + (((sv[8] + sv[9]) + (sv[10] + sv[11])) + ((sv[12] + sv[13]) + (sv[14] + sv[15])));
;         l += ps;
;     }
; #pragma unroll
;     for (int k4 = 0; k4 < 4; ++k4) {
;         const int k2 = k4 >> 1, o8 = 8 * (k4 & 1);
;         u32x4 pk;
;         pk.x = pk2(st[k2][o8 + 0], st[k2][o8 + 1]); pk.y = pk2(st[k2][o8 + 2], st[k2][o8 + 3]);
;         pk.z = pk2(st[k2][o8 + 4], st[k2][o8 + 5]); pk.w = pk2(st[k2][o8 + 6], st[k2][o8 + 7]);
;         pb[k4] = __builtin_bit_cast(bf16x8, pk);
;     }
.Lpipe_norescale_l:
	v_exp_f32_e32 v82, v82
	v_exp_f32_e32 v83, v83
	v_exp_f32_e32 v84, v84
	v_exp_f32_e32 v85, v85
	v_exp_f32_e32 v86, v86
	v_exp_f32_e32 v87, v87
	v_exp_f32_e32 v88, v88
	v_exp_f32_e32 v89, v89
	v_exp_f32_e32 v90, v90
	v_exp_f32_e32 v91, v91
	v_exp_f32_e32 v92, v92
	v_exp_f32_e32 v93, v93
	v_exp_f32_e32 v94, v94
	v_exp_f32_e32 v95, v95
	v_exp_f32_e32 v96, v96
	v_exp_f32_e32 v97, v97
	v_exp_f32_e32 v66, v66
	v_exp_f32_e32 v67, v67
	v_exp_f32_e32 v68, v68
	v_exp_f32_e32 v69, v69
	v_exp_f32_e32 v70, v70
	v_exp_f32_e32 v71, v71
	v_exp_f32_e32 v72, v72
	v_exp_f32_e32 v73, v73
	v_exp_f32_e32 v74, v74
	v_exp_f32_e32 v75, v75
	v_exp_f32_e32 v76, v76
	v_exp_f32_e32 v77, v77
	v_exp_f32_e32 v78, v78
	v_exp_f32_e32 v79, v79
	v_exp_f32_e32 v80, v80
	v_exp_f32_e32 v81, v81
	v_cvt_pk_bf16_f32 v216, v82, v83
	v_cvt_pk_bf16_f32 v217, v84, v85
	v_cvt_pk_bf16_f32 v218, v86, v87
	v_cvt_pk_bf16_f32 v219, v88, v89
	v_cvt_pk_bf16_f32 v220, v90, v91
	v_cvt_pk_bf16_f32 v221, v92, v93
	v_cvt_pk_bf16_f32 v222, v94, v95
	v_cvt_pk_bf16_f32 v223, v96, v97
	v_cvt_pk_bf16_f32 v224, v66, v67
	v_cvt_pk_bf16_f32 v225, v68, v69
	v_cvt_pk_bf16_f32 v226, v70, v71
	v_cvt_pk_bf16_f32 v227, v72, v73
	v_cvt_pk_bf16_f32 v228, v74, v75
	v_cvt_pk_bf16_f32 v229, v76, v77
	v_cvt_pk_bf16_f32 v230, v78, v79
	v_cvt_pk_bf16_f32 v231, v80, v81
	v_pk_add_f32 v[68:69], v[84:85], v[68:69]
	v_pk_add_f32 v[66:67], v[82:83], v[66:67]
	v_pk_add_f32 v[72:73], v[88:89], v[72:73]
	v_pk_add_f32 v[70:71], v[86:87], v[70:71]
	v_add_f32_e32 v66, v66, v67
	v_add_f32_e32 v67, v68, v69
	v_add_f32_e32 v66, v66, v67
	v_add_f32_e32 v67, v70, v71
	v_add_f32_e32 v68, v72, v73
	v_pk_add_f32 v[76:77], v[92:93], v[76:77]
	v_pk_add_f32 v[74:75], v[90:91], v[74:75]
	v_add_f32_e32 v67, v67, v68
	v_pk_add_f32 v[80:81], v[96:97], v[80:81]
	v_pk_add_f32 v[78:79], v[94:95], v[78:79]
	v_add_f32_e32 v66, v66, v67
	v_add_f32_e32 v67, v74, v75
	v_add_f32_e32 v68, v76, v77
	v_add_f32_e32 v67, v67, v68
	v_add_f32_e32 v68, v78, v79
	v_add_f32_e32 v69, v80, v81
	v_add_f32_e32 v68, v68, v69
	v_add_f32_e32 v67, v67, v68
	v_add_f32_e32 v66, v66, v67
	v_add_f32_e32 v1, v1, v66
	v_add_u32_e32 v158, 64, v158
	s_mov_b32 s13, s7
	s_add_i32 s4, s7, 1
	s_cmp_lg_u32 s7, 2
	s_cselect_b32 s7, s4, 0
	s_add_i32 s12, s12, 1
	s_cmp_eq_u32 s11, s12
	s_cbranch_scc1 .Lpipe_final
	s_barrier
	s_mul_i32 s98, s13, 0x8c00
	v_add3_u32 v185, s98, v155, v154
	ds_read_b128 v[160:163], v185
	ds_read_b128 v[164:167], v185 offset:32
	ds_read_b128 v[168:171], v185 offset:8704
	ds_read_b128 v[196:199], v185 offset:8736
	s_waitcnt lgkmcnt(11)
	v_mfma_f32_32x32x16_bf16 v[50:65], v[172:175], v[216:219], v[50:65]
	s_waitcnt lgkmcnt(10)
	v_mfma_f32_32x32x16_bf16 v[34:49], v[176:179], v[216:219], v[34:49]
	s_waitcnt lgkmcnt(9)
	v_mfma_f32_32x32x16_bf16 v[18:33], v[180:183], v[216:219], v[18:33]
	s_waitcnt lgkmcnt(8)
	v_mfma_f32_32x32x16_bf16 v[2:17], v[192:195], v[216:219], v[2:17]
	ds_read_b128 v[172:175], v185 offset:64
	ds_read_b128 v[176:179], v185 offset:96
	ds_read_b128 v[180:183], v185 offset:8768
	ds_read_b128 v[192:195], v185 offset:8800
	s_waitcnt lgkmcnt(11)
	v_mfma_f32_32x32x16_bf16 v[50:65], v[200:203], v[220:223], v[50:65]
	s_waitcnt lgkmcnt(10)
	v_mfma_f32_32x32x16_bf16 v[34:49], v[204:207], v[220:223], v[34:49]
	s_waitcnt lgkmcnt(9)
	v_mfma_f32_32x32x16_bf16 v[18:33], v[208:211], v[220:223], v[18:33]
	s_waitcnt lgkmcnt(8)
	v_mfma_f32_32x32x16_bf16 v[2:17], v[212:215], v[220:223], v[2:17]
	ds_read_b128 v[200:203], v191 offset:17472
	ds_read_b128 v[204:207], v191 offset:22080
	ds_read_b128 v[208:211], v191 offset:26688
	ds_read_b128 v[212:215], v191 offset:31296
	s_waitcnt lgkmcnt(11)
	v_mfma_f32_32x32x16_bf16 v[82:97], v[160:163], v[100:103], v[240:255]
	s_waitcnt lgkmcnt(9)
	v_mfma_f32_32x32x16_bf16 v[66:81], v[168:171], v[100:103], v[240:255]
	v_mfma_f32_32x32x16_bf16 v[82:97], v[164:167], v[104:107], v[82:97]
	s_waitcnt lgkmcnt(8)
	v_mfma_f32_32x32x16_bf16 v[66:81], v[196:199], v[104:107], v[66:81]
	ds_read_b128 v[160:163], v191 offset:17504
	ds_read_b128 v[164:167], v191 offset:22112
	ds_read_b128 v[168:171], v191 offset:26720
	ds_read_b128 v[196:199], v191 offset:31328
	s_waitcnt lgkmcnt(11)
	v_mfma_f32_32x32x16_bf16 v[82:97], v[172:175], v[108:111], v[82:97]
	s_waitcnt lgkmcnt(9)
	v_mfma_f32_32x32x16_bf16 v[66:81], v[180:183], v[108:111], v[66:81]
	v_mfma_f32_32x32x16_bf16 v[82:97], v[176:179], v[112:115], v[82:97]
	s_waitcnt lgkmcnt(8)
	v_mfma_f32_32x32x16_bf16 v[66:81], v[192:195], v[112:115], v[66:81]
	s_add_i32 s14, s12, 0x42
	s_cmp_ge_i32 s14, s6
	s_cbranch_scc1 .Lpipe_nost_l
	s_mul_i32 s4, s7, 0x8c00
	s_add_i32 s4, s4, 0
	v_add_u32_e32 v184, s4, v140
	v_add_u32_e32 v185, v184, v139
	v_add_u32_e32 v184, v184, v141
	s_waitcnt vmcnt(3)
	ds_write_b128 v185, v[116:119]
	s_waitcnt vmcnt(2)
	ds_write_b128 v184, v[120:123]
	v_add3_u32 v184, s4, v150, v151
	v_add_u32_e32 v185, v184, v152
	v_add_u32_e32 v184, v184, v153
	v_add_u32_e32 v185, 0x4000, v185
	v_add_u32_e32 v184, 0x4000, v184
	s_waitcnt vmcnt(1)
	ds_write2_b64 v185, v[124:125], v[126:127] offset0:128 offset1:130
	s_waitcnt vmcnt(0)
	ds_write2_b64 v184, v[128:129], v[130:131] offset0:128 offset1:130

; #define LAS __attribute__((address_space(3)))
; #define GRID_BARRIER() { XcdBarrier xb_; xb_.bar = (unsigned*)(p.ws + OFF_XBAR); xb_.x = xb_xcc_id(); xb_.st = (volatile LAS unsigned*)(lds + LDS_ITEM + 16); xcd_barrier(xb_); }
; __global__ void __launch_bounds__(512) hybrid_fwd(Params p) {
;     extern __shared__ __attribute__((aligned(16))) unsigned char lds[];
;     ...
;     run_phase(p, lds, p.phase_lo);
;     ...
;     cg::grid_group grid = cg::this_grid();
;     if (p.phase_lo == 77) grid.sync();
;     {
;         volatile LAS unsigned* st = (volatile LAS unsigned*)(lds + LDS_ITEM + 16);
;         if (threadIdx.x == 0) { st[0] = 0u; st[1] = 0u; }
;         __syncthreads();
;         (void)xcd_barrier_post((unsigned*)(p.ws + OFF_XBAR), st);
;     }
;     ...
;     phase0(p, lds); GRID_BARRIER();
;     phase1(p, lds); GRID_BARRIER();
;     phase15(p, lds); GRID_BARRIER();
;     phase2(p, lds); GRID_BARRIER();
;     phase3(p, lds); GRID_BARRIER();
;     phase4(p, lds);
;     ...
; }
	.amdhsa_kernel _Z10hybrid_fwd6Params
		.amdhsa_group_segment_fixed_size 0
		.amdhsa_private_segment_fixed_size 0
		.amdhsa_kernarg_size 408
		.amdhsa_user_sgpr_count 2
		.amdhsa_user_sgpr_dispatch_ptr 0
		.amdhsa_user_sgpr_queue_ptr 0
		.amdhsa_user_sgpr_kernarg_segment_ptr 1
		.amdhsa_user_sgpr_dispatch_id 0
		.amdhsa_user_sgpr_kernarg_preload_length 0
		.amdhsa_user_sgpr_kernarg_preload_offset 0
		.amdhsa_user_sgpr_private_segment_size 0
		.amdhsa_uses_dynamic_stack 0
		.amdhsa_enable_private_segment 0
		.amdhsa_system_sgpr_workgroup_id_x 1
		.amdhsa_system_sgpr_workgroup_id_y 0
		.amdhsa_system_sgpr_workgroup_id_z 0
		.amdhsa_system_sgpr_workgroup_info 0
		.amdhsa_system_vgpr_workitem_id 2
		.amdhsa_next_free_vgpr 256
		.amdhsa_next_free_sgpr 100
		.amdhsa_accum_offset 256
		.amdhsa_reserve_vcc 1
		.amdhsa_float_round_mode_32 0
		.amdhsa_float_round_mode_16_64 0
		.amdhsa_float_denorm_mode_32 3
		.amdhsa_float_denorm_mode_16_64 3
		.amdhsa_dx10_clamp 1
		.amdhsa_ieee_mode 1
		.amdhsa_fp16_overflow 0
		.amdhsa_tg_split 0
		.amdhsa_exception_fp_ieee_invalid_op 0
		.amdhsa_exception_fp_denorm_src 0
		.amdhsa_exception_fp_ieee_div_zero 0
		.amdhsa_exception_fp_ieee_overflow 0
		.amdhsa_exception_fp_ieee_underflow 0
		.amdhsa_exception_fp_ieee_inexact 0
		.amdhsa_exception_int_div_zero 0
	.end_amdhsa_kernel

; #define LAS __attribute__((address_space(3)))
; #define GRID_BARRIER() { XcdBarrier xb_; xb_.bar = (unsigned*)(p.ws + OFF_XBAR); xb_.x = xb_xcc_id(); xb_.st = (volatile LAS unsigned*)(lds + LDS_ITEM + 16); xcd_barrier(xb_); }
; __global__ void __launch_bounds__(512) hybrid_fwd(Params p) {
;     extern __shared__ __attribute__((aligned(16))) unsigned char lds[];
;     ...
;     run_phase(p, lds, p.phase_lo);
;     ...
;     cg::grid_group grid = cg::this_grid();
;     if (p.phase_lo == 77) grid.sync();
;     {
;         volatile LAS unsigned* st = (volatile LAS unsigned*)(lds + LDS_ITEM + 16);
;         if (threadIdx.x == 0) { st[0] = 0u; st[1] = 0u; }
;         __syncthreads();
;         (void)xcd_barrier_post((unsigned*)(p.ws + OFF_XBAR), st);
;     }
;     ...
;     phase0(p, lds); GRID_BARRIER();
;     phase1(p, lds); GRID_BARRIER();
;     phase15(p, lds); GRID_BARRIER();
;     phase2(p, lds); GRID_BARRIER();
;     phase3(p, lds); GRID_BARRIER();
;     phase4(p, lds);
;     ...
; }
amdhsa.kernels:
  - .agpr_count:     0
    .args:
      - .offset:         0
        .size:           152
        .value_kind:     by_value
      - .offset:         152
        .size:           4
        .value_kind:     hidden_block_count_x
      - .offset:         156
        .size:           4
        .value_kind:     hidden_block_count_y
      - .offset:         160
        .size:           4
        .value_kind:     hidden_block_count_z
      - .offset:         164
        .size:           2
        .value_kind:     hidden_group_size_x
      - .offset:         166
        .size:           2
        .value_kind:     hidden_group_size_y
      - .offset:         168
        .size:           2
        .value_kind:     hidden_group_size_z
      - .offset:         170
        .size:           2
        .value_kind:     hidden_remainder_x
      - .offset:         172
        .size:           2
        .value_kind:     hidden_remainder_y
      - .offset:         174
        .size:           2
        .value_kind:     hidden_remainder_z
      - .offset:         192
        .size:           8
        .value_kind:     hidden_global_offset_x
      - .offset:         200
        .size:           8
        .value_kind:     hidden_global_offset_y
      - .offset:         208
        .size:           8
        .value_kind:     hidden_global_offset_z
      - .offset:         216
        .size:           2
        .value_kind:     hidden_grid_dims
      - .offset:         240
        .size:           8
        .value_kind:     hidden_multigrid_sync_arg
      - .offset:         272
        .size:           4
        .value_kind:     hidden_dynamic_lds_size
    .group_segment_fixed_size: 0
    .kernarg_segment_align: 8
    .kernarg_segment_size: 408
    .language:       OpenCL C
    .language_version:
      - 2
      - 0
    .max_flat_workgroup_size: 512
    .name:           _Z10hybrid_fwd6Params
    .private_segment_fixed_size: 0
    .sgpr_count:     106
    .sgpr_spill_count: 39
    .symbol:         _Z10hybrid_fwd6Params.kd
    .uniform_work_group_size: 1
    .uses_dynamic_stack: false
    .vgpr_count:     256
    .vgpr_spill_count: 0
    .wavefront_size: 64
